# P5 residual epilogue: 16-deep pipelined residual loads instead of serialized load-wait-add-store chain
# speedup vs baseline: 1.0088x; 1.0088x over previous
;     __device__ __forceinline__ void operator()(const f32x4 (&acc)[2][2][4][2], const Unit& u, int wr, int wc, int fr, int fq) const {
;         const int col0 = u.pn * BM + wc * 32 + 4 * fq; const int rbase = remap ? ((((u.pm >> 3) & 3) << 12) + (u.pm >> 5) * 2048 + (u.pm & 7) * BM) : u.pm * BM;
; #pragma unroll
;         for (int ai = 0; ai < 2; ++ai)
; #pragma unroll
;             for (int m = 0; m < 4; ++m) { const size_t off = (size_t)(rbase + ai * HALF + wr * 64 + m * 16 + fr) * ldc + col0;
; #pragma unroll
;                 for (int bj = 0; bj < 2; ++bj)
; #pragma unroll
;                     for (int n = 0; n < 2; ++n) { const f32x4 bs = __builtin_nontemporal_load((const f32x4*)(base + off + bj * HALF + n * 16)); *(f32x4*)(out + off + bj * HALF + n * 16) = bs + acc[ai][bj][m][n]; } }
.LBB0_333:
	v_lshl_add_u32 v146, s54, 8, v149
	v_lshl_or_b32 v144, s55, 8, v151
	s_and_b64 vcc, exec, s[6:7]
	s_mov_b64 s[6:7], -1
	v_lshlrev_b32_e32 v145, 2, v144
	v_or_b32_e32 v147, 16, v146
	v_lshl_add_u32 v147, v147, 12, v145
	v_or_b32_e32 v155, 32, v146
	v_lshl_add_u32 v155, v155, 12, v145
	v_or_b32_e32 v156, 48, v146
	v_lshl_add_u32 v156, v156, 12, v145
	v_add_u32_e32 v157, 0x80, v146
	v_lshl_add_u32 v157, v157, 12, v145
	v_add_u32_e32 v158, 0x90, v146
	v_lshl_add_u32 v158, v158, 12, v145
	v_add_u32_e32 v159, 0xa0, v146
	v_lshl_add_u32 v159, v159, 12, v145
	v_add_u32_e32 v160, 0xb0, v146
	v_lshl_add_u32 v160, v160, 12, v145
	v_lshl_add_u32 v146, v146, 12, v145
	global_load_dwordx4 v[164:167], v146, s[10:11] nt
	global_load_dwordx4 v[168:171], v146, s[10:11] offset:64 nt
	global_load_dwordx4 v[172:175], v146, s[10:11] offset:512 nt
	global_load_dwordx4 v[176:179], v146, s[10:11] offset:576 nt
	global_load_dwordx4 v[180:183], v147, s[10:11] nt
	global_load_dwordx4 v[184:187], v147, s[10:11] offset:64 nt
	global_load_dwordx4 v[188:191], v147, s[10:11] offset:512 nt
	global_load_dwordx4 v[192:195], v147, s[10:11] offset:576 nt
	global_load_dwordx4 v[196:199], v155, s[10:11] nt
	global_load_dwordx4 v[200:203], v155, s[10:11] offset:64 nt
	global_load_dwordx4 v[204:207], v155, s[10:11] offset:512 nt
	global_load_dwordx4 v[208:211], v155, s[10:11] offset:576 nt
	global_load_dwordx4 v[212:215], v156, s[10:11] nt
	global_load_dwordx4 v[216:219], v156, s[10:11] offset:64 nt
	global_load_dwordx4 v[220:223], v156, s[10:11] offset:512 nt
	global_load_dwordx4 v[224:227], v156, s[10:11] offset:576 nt
	s_waitcnt vmcnt(15)
	v_pk_add_f32 v[124:125], v[124:125], v[164:165]
	v_pk_add_f32 v[126:127], v[126:127], v[166:167]
	global_store_dwordx4 v146, v[124:127], s[12:13]
	global_load_dwordx4 v[164:167], v157, s[10:11] nt
	s_waitcnt vmcnt(16)
	v_pk_add_f32 v[120:121], v[120:121], v[168:169]
	v_pk_add_f32 v[122:123], v[122:123], v[170:171]
	global_store_dwordx4 v146, v[120:123], s[12:13] offset:64
	global_load_dwordx4 v[168:171], v157, s[10:11] offset:64 nt
	s_waitcnt vmcnt(17)
	v_pk_add_f32 v[116:117], v[116:117], v[172:173]
	v_pk_add_f32 v[118:119], v[118:119], v[174:175]
	global_store_dwordx4 v146, v[116:119], s[12:13] offset:512
	global_load_dwordx4 v[172:175], v157, s[10:11] offset:512 nt
	s_waitcnt vmcnt(18)
	v_pk_add_f32 v[104:105], v[104:105], v[176:177]
	v_pk_add_f32 v[106:107], v[106:107], v[178:179]
	global_store_dwordx4 v146, v[104:107], s[12:13] offset:576
	global_load_dwordx4 v[176:179], v157, s[10:11] offset:576 nt
	s_waitcnt vmcnt(19)
	v_pk_add_f32 v[112:113], v[112:113], v[180:181]
	v_pk_add_f32 v[114:115], v[114:115], v[182:183]
	global_store_dwordx4 v147, v[112:115], s[12:13]
	global_load_dwordx4 v[180:183], v158, s[10:11] nt
	s_waitcnt vmcnt(20)
	v_pk_add_f32 v[108:109], v[108:109], v[184:185]
	v_pk_add_f32 v[110:111], v[110:111], v[186:187]
	global_store_dwordx4 v147, v[108:111], s[12:13] offset:64
	global_load_dwordx4 v[184:187], v158, s[10:11] offset:64 nt
	s_waitcnt vmcnt(21)
	v_pk_add_f32 v[100:101], v[100:101], v[188:189]
	v_pk_add_f32 v[102:103], v[102:103], v[190:191]
	global_store_dwordx4 v147, v[100:103], s[12:13] offset:512
	global_load_dwordx4 v[188:191], v158, s[10:11] offset:512 nt
	s_waitcnt vmcnt(22)
	v_pk_add_f32 v[88:89], v[88:89], v[192:193]
	v_pk_add_f32 v[90:91], v[90:91], v[194:195]
	global_store_dwordx4 v147, v[88:91], s[12:13] offset:576
	global_load_dwordx4 v[192:195], v158, s[10:11] offset:576 nt
	s_waitcnt vmcnt(23)
	v_pk_add_f32 v[96:97], v[96:97], v[196:197]
	v_pk_add_f32 v[98:99], v[98:99], v[198:199]
	global_store_dwordx4 v155, v[96:99], s[12:13]
	global_load_dwordx4 v[196:199], v159, s[10:11] nt
	s_waitcnt vmcnt(24)
	v_pk_add_f32 v[92:93], v[92:93], v[200:201]
	v_pk_add_f32 v[94:95], v[94:95], v[202:203]
	global_store_dwordx4 v155, v[92:95], s[12:13] offset:64
	global_load_dwordx4 v[200:203], v159, s[10:11] offset:64 nt
	s_waitcnt vmcnt(25)
;     __device__ __forceinline__ void operator()(const f32x4 (&acc)[2][2][4][2], const Unit& u, int wr, int wc, int fr, int fq) const {
;         const int col0 = u.pn * BM + wc * 32 + 4 * fq; const int rbase = remap ? ((((u.pm >> 3) & 3) << 12) + (u.pm >> 5) * 2048 + (u.pm & 7) * BM) : u.pm * BM;
; #pragma unroll
;         for (int ai = 0; ai < 2; ++ai)
; #pragma unroll
;             for (int m = 0; m < 4; ++m) { const size_t off = (size_t)(rbase + ai * HALF + wr * 64 + m * 16 + fr) * ldc + col0;
; #pragma unroll
;                 for (int bj = 0; bj < 2; ++bj)
; #pragma unroll
;                     for (int n = 0; n < 2; ++n) { const f32x4 bs = __builtin_nontemporal_load((const f32x4*)(base + off + bj * HALF + n * 16)); *(f32x4*)(out + off + bj * HALF + n * 16) = bs + acc[ai][bj][m][n]; } }
	v_pk_add_f32 v[84:85], v[84:85], v[204:205]
	v_pk_add_f32 v[86:87], v[86:87], v[206:207]
	global_store_dwordx4 v155, v[84:87], s[12:13] offset:512
	global_load_dwordx4 v[204:207], v159, s[10:11] offset:512 nt
	s_waitcnt vmcnt(26)
	v_pk_add_f32 v[72:73], v[72:73], v[208:209]
	v_pk_add_f32 v[74:75], v[74:75], v[210:211]
	global_store_dwordx4 v155, v[72:75], s[12:13] offset:576
	global_load_dwordx4 v[208:211], v159, s[10:11] offset:576 nt
	s_waitcnt vmcnt(27)
	v_pk_add_f32 v[80:81], v[80:81], v[212:213]
	v_pk_add_f32 v[82:83], v[82:83], v[214:215]
	global_store_dwordx4 v156, v[80:83], s[12:13]
	global_load_dwordx4 v[212:215], v160, s[10:11] nt
	s_waitcnt vmcnt(28)
	v_pk_add_f32 v[76:77], v[76:77], v[216:217]
	v_pk_add_f32 v[78:79], v[78:79], v[218:219]
	global_store_dwordx4 v156, v[76:79], s[12:13] offset:64
	global_load_dwordx4 v[216:219], v160, s[10:11] offset:64 nt
	s_waitcnt vmcnt(29)
	v_pk_add_f32 v[68:69], v[68:69], v[220:221]
	v_pk_add_f32 v[70:71], v[70:71], v[222:223]
	global_store_dwordx4 v156, v[68:71], s[12:13] offset:512
	global_load_dwordx4 v[220:223], v160, s[10:11] offset:512 nt
	s_waitcnt vmcnt(30)
	v_pk_add_f32 v[64:65], v[64:65], v[224:225]
	v_pk_add_f32 v[66:67], v[66:67], v[226:227]
	global_store_dwordx4 v156, v[64:67], s[12:13] offset:576
	global_load_dwordx4 v[224:227], v160, s[10:11] offset:576 nt
	s_waitcnt vmcnt(30)
	v_pk_add_f32 v[60:61], v[60:61], v[164:165]
	v_pk_add_f32 v[62:63], v[62:63], v[166:167]
	global_store_dwordx4 v157, v[60:63], s[12:13]
	s_waitcnt vmcnt(29)
	v_pk_add_f32 v[56:57], v[56:57], v[168:169]
	v_pk_add_f32 v[58:59], v[58:59], v[170:171]
	global_store_dwordx4 v157, v[56:59], s[12:13] offset:64
	s_waitcnt vmcnt(28)
	v_pk_add_f32 v[52:53], v[52:53], v[172:173]
	v_pk_add_f32 v[54:55], v[54:55], v[174:175]
	global_store_dwordx4 v157, v[52:55], s[12:13] offset:512
	s_waitcnt vmcnt(27)
	v_pk_add_f32 v[40:41], v[40:41], v[176:177]
	v_pk_add_f32 v[42:43], v[42:43], v[178:179]
	global_store_dwordx4 v157, v[40:43], s[12:13] offset:576
	s_waitcnt vmcnt(26)
	v_pk_add_f32 v[48:49], v[48:49], v[180:181]
	v_pk_add_f32 v[50:51], v[50:51], v[182:183]
	global_store_dwordx4 v158, v[48:51], s[12:13]
	s_waitcnt vmcnt(25)
	v_pk_add_f32 v[44:45], v[44:45], v[184:185]
	v_pk_add_f32 v[46:47], v[46:47], v[186:187]
	global_store_dwordx4 v158, v[44:47], s[12:13] offset:64
	s_waitcnt vmcnt(24)
	v_pk_add_f32 v[36:37], v[36:37], v[188:189]
	v_pk_add_f32 v[38:39], v[38:39], v[190:191]
	global_store_dwordx4 v158, v[36:39], s[12:13] offset:512
	s_waitcnt vmcnt(23)
	v_pk_add_f32 v[24:25], v[24:25], v[192:193]
	v_pk_add_f32 v[26:27], v[26:27], v[194:195]
	global_store_dwordx4 v158, v[24:27], s[12:13] offset:576
	s_waitcnt vmcnt(22)
	v_pk_add_f32 v[32:33], v[32:33], v[196:197]
	v_pk_add_f32 v[34:35], v[34:35], v[198:199]
	global_store_dwordx4 v159, v[32:35], s[12:13]
	s_waitcnt vmcnt(21)
	v_pk_add_f32 v[28:29], v[28:29], v[200:201]
	v_pk_add_f32 v[30:31], v[30:31], v[202:203]
	global_store_dwordx4 v159, v[28:31], s[12:13] offset:64
	s_waitcnt vmcnt(20)
	v_pk_add_f32 v[20:21], v[20:21], v[204:205]
	v_pk_add_f32 v[22:23], v[22:23], v[206:207]
	global_store_dwordx4 v159, v[20:23], s[12:13] offset:512
	s_waitcnt vmcnt(19)
	v_pk_add_f32 v[8:9], v[8:9], v[208:209]
	v_pk_add_f32 v[10:11], v[10:11], v[210:211]
	global_store_dwordx4 v159, v[8:11], s[12:13] offset:576
	s_waitcnt vmcnt(18)
	v_pk_add_f32 v[16:17], v[16:17], v[212:213]
	v_pk_add_f32 v[18:19], v[18:19], v[214:215]
	global_store_dwordx4 v160, v[16:19], s[12:13]
	s_waitcnt vmcnt(17)
	v_pk_add_f32 v[12:13], v[12:13], v[216:217]
	v_pk_add_f32 v[14:15], v[14:15], v[218:219]
	global_store_dwordx4 v160, v[12:15], s[12:13] offset:64
	s_waitcnt vmcnt(16)
	v_pk_add_f32 v[4:5], v[4:5], v[220:221]
	v_pk_add_f32 v[6:7], v[6:7], v[222:223]
	global_store_dwordx4 v160, v[4:7], s[12:13] offset:512
	s_waitcnt vmcnt(15)
	v_pk_add_f32 v[0:1], v[0:1], v[224:225]
	v_pk_add_f32 v[2:3], v[2:3], v[226:227]
	global_store_dwordx4 v160, v[0:3], s[12:13] offset:576
	s_cbranch_vccnz .LBB0_320
	s_andn2_b64 vcc, exec, s[14:15]
	s_cbranch_vccnz .LBB0_319
	s_barrier
	s_branch .LBB0_319
